# MoBA V tile staged by LDS-DMA (256B rows, 32B-slot XOR swizzle, 8 read bases), DMA offsets hoisted out of the tile loop
# baseline (speedup 1.0000x reference)
.LBB0_877:
	s_waitcnt lgkmcnt(0)
	v_max3_f32 v70, v11, v126, v127
	v_sub_f32_e32 v68, v113, v70
	v_exp_f32_e32 v68, v68
	v_sub_f32_e32 v69, v109, v70
	v_exp_f32_e32 v69, v69
	v_sub_f32_e32 v71, v73, v70
	v_exp_f32_e32 v71, v71
	v_sub_f32_e32 v72, v72, v70
	v_exp_f32_e32 v73, v72
	v_add_f32_e32 v72, 0, v68
	v_add_f32_e32 v72, v69, v72
	v_add_f32_e32 v72, v71, v72
	v_add_f32_e32 v76, v73, v72
	v_cvt_pk_bf16_f32 v72, v68, v69
	v_sub_f32_e32 v68, v112, v70
	v_exp_f32_e32 v68, v68
	v_sub_f32_e32 v69, v108, v70
	v_cvt_pk_bf16_f32 v73, v71, v73
	v_exp_f32_e32 v69, v69
	v_sub_f32_e32 v71, v75, v70
	v_exp_f32_e32 v71, v71
	v_sub_f32_e32 v74, v74, v70
	v_exp_f32_e32 v75, v74
	v_add_f32_e32 v74, v68, v76
	v_add_f32_e32 v74, v69, v74
	v_add_f32_e32 v74, v71, v74
	v_add_f32_e32 v76, v75, v74
	v_cvt_pk_bf16_f32 v74, v68, v69
	v_sub_f32_e32 v68, v111, v70
	v_exp_f32_e32 v68, v68
	v_sub_f32_e32 v69, v107, v70
	v_cvt_pk_bf16_f32 v75, v71, v75
	v_exp_f32_e32 v69, v69
	v_add_f32_e32 v71, v68, v76
	v_sub_f32_e32 v76, v104, v70
	v_exp_f32_e32 v76, v76
	v_sub_f32_e32 v8, v8, v70
	v_exp_f32_e32 v8, v8
	v_sub_f32_e32 v77, v114, v70
	v_exp_f32_e32 v77, v77
	v_add_f32_e32 v71, v69, v71
	v_add_f32_e32 v71, v76, v71
	v_add_f32_e32 v71, v8, v71
	v_cvt_pk_bf16_f32 v68, v68, v69
	v_cvt_pk_bf16_f32 v69, v76, v8
	v_add_f32_e32 v8, v77, v71
	v_sub_f32_e32 v71, v110, v70
	v_exp_f32_e32 v71, v71
	v_sub_f32_e32 v76, v106, v70
	v_exp_f32_e32 v76, v76
	v_sub_f32_e32 v11, v11, v70
	v_sub_f32_e32 v70, v105, v70
	v_exp_f32_e32 v78, v70
	v_add_f32_e32 v8, v71, v8
	v_add_f32_e32 v70, v76, v8
	v_exp_f32_e32 v8, v11
	v_add_f32_e32 v104, v78, v70
	v_max_f32_e32 v11, v89, v89
	v_cvt_pk_bf16_f32 v70, v77, v71
	v_fmac_f32_e32 v104, v10, v8
	v_max_f32_e32 v10, v88, v88
	v_cvt_pk_bf16_f32 v71, v76, v78
	v_max_f32_e32 v10, v11, v10
	v_max_f32_e32 v11, v90, v90
	v_max_f32_e32 v76, v92, v92
	v_max_f32_e32 v11, v76, v11
	v_max3_f32 v10, v94, v91, v10
	v_max3_f32 v11, v99, v95, v11
	v_max3_f32 v10, v10, s3, v11
	v_max_f32_e32 v11, v93, v93
	v_max_f32_e32 v76, v96, v96
	v_max_f32_e32 v11, v76, v11
	v_max_f32_e32 v76, v97, v97
	v_max_f32_e32 v77, v100, v100
	v_max_f32_e32 v76, v77, v76
	v_max3_f32 v11, v101, v98, v11
	v_max3_f32 v76, v103, v102, v76
	v_max3_f32 v10, v10, v11, v76
	ds_bpermute_b32 v11, v175, v10
	v_pk_mul_f32 v[66:67], v[66:67], v[8:9] op_sel_hi:[1,0]
	v_pk_mul_f32 v[64:65], v[64:65], v[8:9] op_sel_hi:[1,0]
	v_pk_mul_f32 v[62:63], v[62:63], v[8:9] op_sel_hi:[1,0]
	v_pk_mul_f32 v[60:61], v[60:61], v[8:9] op_sel_hi:[1,0]
	s_waitcnt lgkmcnt(0)
	v_max_f32_e32 v10, v10, v11
	ds_bpermute_b32 v11, v174, v10
	v_pk_mul_f32 v[58:59], v[58:59], v[8:9] op_sel_hi:[1,0]
	v_pk_mul_f32 v[56:57], v[56:57], v[8:9] op_sel_hi:[1,0]
	v_pk_mul_f32 v[54:55], v[54:55], v[8:9] op_sel_hi:[1,0]
	v_pk_mul_f32 v[52:53], v[52:53], v[8:9] op_sel_hi:[1,0]
	v_pk_mul_f32 v[50:51], v[50:51], v[8:9] op_sel_hi:[1,0]
	v_pk_mul_f32 v[48:49], v[48:49], v[8:9] op_sel_hi:[1,0]
	v_pk_mul_f32 v[46:47], v[46:47], v[8:9] op_sel_hi:[1,0]
	v_pk_mul_f32 v[44:45], v[44:45], v[8:9] op_sel_hi:[1,0]
	v_pk_mul_f32 v[42:43], v[42:43], v[8:9] op_sel_hi:[1,0]
	v_pk_mul_f32 v[40:41], v[40:41], v[8:9] op_sel_hi:[1,0]
	v_pk_mul_f32 v[38:39], v[38:39], v[8:9] op_sel_hi:[1,0]
	v_pk_mul_f32 v[36:37], v[36:37], v[8:9] op_sel_hi:[1,0]
	s_waitcnt lgkmcnt(0)
	v_max3_f32 v8, v181, v10, v11
	v_sub_f32_e32 v11, v94, v8
	v_exp_f32_e32 v11, v11
	v_sub_f32_e32 v76, v91, v8
	v_exp_f32_e32 v76, v76
	v_sub_f32_e32 v77, v89, v8
	v_exp_f32_e32 v77, v77
	v_sub_f32_e32 v78, v88, v8
	v_exp_f32_e32 v78, v78
	v_add_f32_e32 v79, 0, v11
	v_add_f32_e32 v79, v76, v79
	v_cvt_pk_bf16_f32 v80, v11, v76
	v_sub_f32_e32 v11, v99, v8
	v_sub_f32_e32 v76, v95, v8
	v_add_f32_e32 v79, v77, v79
	v_exp_f32_e32 v11, v11
	v_exp_f32_e32 v76, v76
	v_add_f32_e32 v79, v78, v79
	v_cvt_pk_bf16_f32 v81, v77, v78
	v_sub_f32_e32 v77, v92, v8
	v_sub_f32_e32 v78, v90, v8
	v_exp_f32_e32 v77, v77
	v_exp_f32_e32 v78, v78
	v_add_f32_e32 v79, v11, v79
	v_cvt_pk_bf16_f32 v82, v11, v76
	v_sub_f32_e32 v11, v101, v8
	v_add_f32_e32 v79, v76, v79
	v_exp_f32_e32 v11, v11
	v_sub_f32_e32 v76, v98, v8
	v_add_f32_e32 v79, v77, v79
	v_cvt_pk_bf16_f32 v83, v77, v78
	v_exp_f32_e32 v76, v76
	v_sub_f32_e32 v77, v96, v8
	v_add_f32_e32 v79, v78, v79
	v_exp_f32_e32 v77, v77
	v_sub_f32_e32 v78, v93, v8
	v_exp_f32_e32 v78, v78
	v_add_f32_e32 v79, v11, v79
	v_add_f32_e32 v79, v76, v79
	v_add_f32_e32 v79, v77, v79
	v_cvt_pk_bf16_f32 v76, v11, v76
	v_sub_f32_e32 v11, v103, v8
	v_add_f32_e32 v79, v78, v79
	v_cvt_pk_bf16_f32 v77, v77, v78
	v_exp_f32_e32 v11, v11
	v_sub_f32_e32 v78, v102, v8
	v_exp_f32_e32 v78, v78
	v_sub_f32_e32 v84, v100, v8
	v_sub_f32_e32 v10, v181, v8
	v_exp_f32_e32 v84, v84
	v_sub_f32_e32 v8, v97, v8
	v_exp_f32_e32 v8, v8
	v_add_f32_e32 v79, v11, v79
	v_add_f32_e32 v79, v78, v79
	s_mulk_i32 s6, 0x4800
	v_add_f32_e32 v79, v84, v79
	v_add_u32_e32 v106, s6, v176
	v_xor_b32_e32 v226, 0x20, v106
	v_xor_b32_e32 v227, 0x40, v106
	v_xor_b32_e32 v228, 0x60, v106
	v_xor_b32_e32 v229, 0x80, v106
	v_xor_b32_e32 v230, 0xa0, v106
	v_xor_b32_e32 v231, 0xc0, v106
	v_xor_b32_e32 v232, 0xe0, v106
	v_add_f32_e32 v105, v8, v79
	v_cvt_pk_bf16_f32 v79, v84, v8
	v_exp_f32_e32 v8, v10
	ds_read_b64_tr_b16 v[86:87], v106 offset:38912
	ds_read_b64_tr_b16 v[84:85], v106 offset:34816
	ds_read_b64_tr_b16 v[88:89], v226 offset:34816
	ds_read_b64_tr_b16 v[92:93], v227 offset:34816
	ds_read_b64_tr_b16 v[96:97], v228 offset:34816
	ds_read_b64_tr_b16 v[90:91], v226 offset:38912
	ds_read_b64_tr_b16 v[94:95], v227 offset:38912
	ds_read_b64_tr_b16 v[98:99], v228 offset:38912
	s_waitcnt lgkmcnt(6)
	v_mfma_f32_16x16x32_bf16 v[64:67], v[84:87], v[72:75], v[64:67]
	v_mul_f32_e64 v30, v30, v8
	v_mul_f32_e64 v31, v31, v8
	v_pk_mul_f32 v[28:29], v[28:29], v[8:9] op_sel_hi:[1,0]
	v_pk_mul_f32 v[22:23], v[22:23], v[8:9] op_sel_hi:[1,0]
	v_pk_mul_f32 v[20:21], v[20:21], v[8:9] op_sel_hi:[1,0]
	v_pk_mul_f32 v[6:7], v[6:7], v[8:9] op_sel_hi:[1,0]
	v_pk_mul_f32 v[4:5], v[4:5], v[8:9] op_sel_hi:[1,0]
	v_mfma_f32_16x16x32_bf16 v[28:31], v[84:87], v[80:83], v[28:31]
	v_mul_f32_e64 v14, v14, v8
	v_mul_f32_e64 v15, v15, v8
	v_pk_mul_f32 v[12:13], v[12:13], v[8:9] op_sel_hi:[1,0]
	v_cvt_pk_bf16_f32 v78, v11, v78
	s_waitcnt lgkmcnt(2)
	v_mfma_f32_16x16x32_bf16 v[60:63], v[88:91], v[72:75], v[60:63]
	v_mul_f32_e64 v34, v34, v8
	v_mul_f32_e64 v35, v35, v8
	v_pk_mul_f32 v[32:33], v[32:33], v[8:9] op_sel_hi:[1,0]
	v_pk_mul_f32 v[26:27], v[26:27], v[8:9] op_sel_hi:[1,0]
	v_mfma_f32_16x16x32_bf16 v[20:23], v[88:91], v[80:83], v[20:23]
	v_mul_f32_e64 v24, v24, v8
	v_mul_f32_e64 v25, v25, v8
	v_pk_mul_f32 v[18:19], v[18:19], v[8:9] op_sel_hi:[1,0]
	v_pk_mul_f32 v[16:17], v[16:17], v[8:9] op_sel_hi:[1,0]
	s_waitcnt lgkmcnt(1)
	v_mfma_f32_16x16x32_bf16 v[56:59], v[92:95], v[72:75], v[56:59]
	v_mul_f32_e64 v2, v2, v8
	v_mul_f32_e64 v3, v3, v8
	v_pk_mul_f32 v[0:1], v[0:1], v[8:9] op_sel_hi:[1,0]
	v_fmac_f32_e32 v105, v177, v8
	v_mfma_f32_16x16x32_bf16 v[4:7], v[92:95], v[80:83], v[4:7]
	ds_read_b64_tr_b16 v[84:85], v229 offset:34816
	ds_read_b64_tr_b16 v[88:89], v230 offset:34816
	ds_read_b64_tr_b16 v[92:93], v231 offset:34816
	ds_read_b64_tr_b16 v[100:101], v232 offset:34816
	ds_read_b64_tr_b16 v[86:87], v229 offset:38912
	ds_read_b64_tr_b16 v[90:91], v230 offset:38912
	ds_read_b64_tr_b16 v[94:95], v231 offset:38912
	ds_read_b64_tr_b16 v[102:103], v232 offset:38912
	s_waitcnt lgkmcnt(8)
	v_mfma_f32_16x16x32_bf16 v[52:55], v[96:99], v[72:75], v[52:55]
	v_mfma_f32_16x16x32_bf16 v[10:13], v[96:99], v[80:83], v[12:15]
	s_waitcnt lgkmcnt(3)
	v_mfma_f32_16x16x32_bf16 v[48:51], v[84:87], v[72:75], v[48:51]
	v_mfma_f32_16x16x32_bf16 v[32:35], v[84:87], v[80:83], v[32:35]
	s_waitcnt lgkmcnt(2)
	v_mfma_f32_16x16x32_bf16 v[44:47], v[88:91], v[72:75], v[44:47]
	v_mfma_f32_16x16x32_bf16 v[24:27], v[88:91], v[80:83], v[24:27]
	s_waitcnt lgkmcnt(1)
	v_mfma_f32_16x16x32_bf16 v[40:43], v[92:95], v[72:75], v[40:43]
	v_mfma_f32_16x16x32_bf16 v[16:19], v[92:95], v[80:83], v[16:19]
	ds_read_b64_tr_b16 v[84:85], v106 offset:43008
	ds_read_b64_tr_b16 v[88:89], v226 offset:43008
	ds_read_b64_tr_b16 v[92:93], v227 offset:43008
	ds_read_b64_tr_b16 v[96:97], v228 offset:43008
	ds_read_b64_tr_b16 v[86:87], v106 offset:47104
	ds_read_b64_tr_b16 v[90:91], v226 offset:47104
	ds_read_b64_tr_b16 v[94:95], v227 offset:47104
	ds_read_b64_tr_b16 v[98:99], v228 offset:47104
	s_waitcnt lgkmcnt(8)
	v_mfma_f32_16x16x32_bf16 v[36:39], v[100:103], v[72:75], v[36:39]
	v_mfma_f32_16x16x32_bf16 v[0:3], v[100:103], v[80:83], v[0:3]
	s_waitcnt lgkmcnt(3)
	v_mfma_f32_16x16x32_bf16 v[64:67], v[84:87], v[68:71], v[64:67]
	v_mfma_f32_16x16x32_bf16 v[28:31], v[84:87], v[76:79], v[28:31]
	s_waitcnt lgkmcnt(2)
	v_mfma_f32_16x16x32_bf16 v[60:63], v[88:91], v[68:71], v[60:63]
	v_mfma_f32_16x16x32_bf16 v[20:23], v[88:91], v[76:79], v[20:23]
	ds_read_b64_tr_b16 v[72:73], v229 offset:43008
	ds_read_b64_tr_b16 v[80:81], v230 offset:43008
	ds_read_b64_tr_b16 v[84:85], v231 offset:43008
	ds_read_b64_tr_b16 v[88:89], v232 offset:43008
	ds_read_b64_tr_b16 v[74:75], v229 offset:47104
	ds_read_b64_tr_b16 v[82:83], v230 offset:47104
	ds_read_b64_tr_b16 v[86:87], v231 offset:47104
	ds_read_b64_tr_b16 v[90:91], v232 offset:47104
	s_waitcnt lgkmcnt(9)
	v_mfma_f32_16x16x32_bf16 v[56:59], v[92:95], v[68:71], v[56:59]
	v_mfma_f32_16x16x32_bf16 v[4:7], v[92:95], v[76:79], v[4:7]
	s_waitcnt lgkmcnt(8)
	v_mfma_f32_16x16x32_bf16 v[52:55], v[96:99], v[68:71], v[52:55]
	v_mfma_f32_16x16x32_bf16 v[12:15], v[96:99], v[76:79], v[10:13]
	s_waitcnt lgkmcnt(3)
	v_mfma_f32_16x16x32_bf16 v[48:51], v[72:75], v[68:71], v[48:51]
	v_mfma_f32_16x16x32_bf16 v[32:35], v[72:75], v[76:79], v[32:35]
	s_waitcnt lgkmcnt(2)
	v_mfma_f32_16x16x32_bf16 v[44:47], v[80:83], v[68:71], v[44:47]
	v_mfma_f32_16x16x32_bf16 v[24:27], v[80:83], v[76:79], v[24:27]
	s_waitcnt lgkmcnt(1)
	v_mfma_f32_16x16x32_bf16 v[40:43], v[84:87], v[68:71], v[40:43]
	v_mfma_f32_16x16x32_bf16 v[16:19], v[84:87], v[76:79], v[16:19]
	s_waitcnt lgkmcnt(0)
	v_mfma_f32_16x16x32_bf16 v[36:39], v[88:91], v[68:71], v[36:39]
	v_mfma_f32_16x16x32_bf16 v[0:3], v[88:91], v[76:79], v[0:3]
	v_mov_b32_e32 v10, v104
	v_mov_b32_e32 v177, v105

.LBB0_892:
	global_load_dwordx4 v[24:27], v[6:7], off offset:16
	global_load_dwordx4 v[28:31], v[6:7], off
	global_load_dwordx4 v[32:35], v[6:7], off offset:-16
	global_load_dwordx4 v[36:39], v[6:7], off offset:-32
	v_add_u32_e32 v52, s5, v8
	v_add_u32_e32 v40, 0x11800, v52
	v_add_u32_e32 v44, 0x12000, v52
	ds_read_b128 v[40:43], v40
	ds_read_b128 v[44:47], v44
	v_add_u32_e32 v53, 0x11810, v52
	v_add_u32_e32 v54, 0x12010, v52
	s_addk_i32 s5, 0x80
	s_waitcnt lgkmcnt(1)
	v_mov_b32_e32 v51, v41
	s_waitcnt lgkmcnt(0)
	v_pk_mov_b32 v[40:41], v[44:45], v[40:41] op_sel:[1,0]
	v_mov_b32_e32 v50, v44
	v_lshl_add_u64 v[6:7], v[6:7], 0, 64
	s_cmpk_lg_i32 s5, 0x200
	s_waitcnt vmcnt(0)
	v_and_b32_e32 v49, 0xffff0000, v36
	v_lshlrev_b32_e32 v48, 16, v36
	v_pk_mul_f32 v[40:41], v[40:41], v[48:49] op_sel:[0,1] op_sel_hi:[1,0]
	v_mov_b32_e32 v36, v46
	v_pk_fma_f32 v[40:41], v[50:51], v[48:49], v[40:41]
	s_nop 0
	v_pk_add_f32 v[4:5], v[4:5], v[40:41]
	v_and_b32_e32 v41, 0xffff0000, v37
	v_lshlrev_b32_e32 v40, 16, v37
	v_mov_b32_e32 v37, v43
	v_pk_mov_b32 v[42:43], v[46:47], v[42:43] op_sel:[1,0]
	s_nop 0
	v_pk_mul_f32 v[42:43], v[42:43], v[40:41] op_sel:[0,1] op_sel_hi:[1,0]
	s_nop 0
	v_pk_fma_f32 v[36:37], v[36:37], v[40:41], v[42:43]
	ds_read_b128 v[40:43], v53
	ds_read_b128 v[44:47], v54
	v_pk_add_f32 v[4:5], v[4:5], v[36:37]
	v_and_b32_e32 v37, 0xffff0000, v38
	v_lshlrev_b32_e32 v36, 16, v38
	s_waitcnt lgkmcnt(1)
	v_mov_b32_e32 v49, v41
	s_waitcnt lgkmcnt(0)
	v_pk_mov_b32 v[40:41], v[44:45], v[40:41] op_sel:[1,0]
	v_mov_b32_e32 v48, v44
	v_pk_mul_f32 v[40:41], v[40:41], v[36:37] op_sel:[0,1] op_sel_hi:[1,0]
	v_mov_b32_e32 v38, v46
	v_pk_fma_f32 v[36:37], v[48:49], v[36:37], v[40:41]
	v_pk_mov_b32 v[40:41], v[46:47], v[42:43] op_sel:[1,0]
	v_pk_add_f32 v[4:5], v[4:5], v[36:37]
	v_and_b32_e32 v37, 0xffff0000, v39
	v_lshlrev_b32_e32 v36, 16, v39
	v_mov_b32_e32 v39, v43
	v_pk_mul_f32 v[40:41], v[40:41], v[36:37] op_sel:[0,1] op_sel_hi:[1,0]
	v_and_b32_e32 v45, 0xffff0000, v32
	v_pk_fma_f32 v[36:37], v[38:39], v[36:37], v[40:41]
	v_add_u32_e32 v40, 0x12020, v52
	v_pk_add_f32 v[4:5], v[4:5], v[36:37]
	v_add_u32_e32 v36, 0x11820, v52
	ds_read_b128 v[36:39], v36
	ds_read_b128 v[40:43], v40
	v_lshlrev_b32_e32 v44, 16, v32
	v_add_u32_e32 v48, 0x11830, v52
	v_add_u32_e32 v49, 0x12030, v52
	s_waitcnt lgkmcnt(1)
	v_mov_b32_e32 v47, v37
	s_waitcnt lgkmcnt(0)
	v_pk_mov_b32 v[36:37], v[40:41], v[36:37] op_sel:[1,0]
	v_mov_b32_e32 v46, v40
	v_pk_mul_f32 v[36:37], v[36:37], v[44:45] op_sel:[0,1] op_sel_hi:[1,0]
	v_mov_b32_e32 v32, v42
	v_pk_fma_f32 v[36:37], v[46:47], v[44:45], v[36:37]
	s_nop 0
	v_pk_add_f32 v[4:5], v[4:5], v[36:37]
	v_and_b32_e32 v37, 0xffff0000, v33
	v_lshlrev_b32_e32 v36, 16, v33
	v_mov_b32_e32 v33, v39
	v_pk_mov_b32 v[38:39], v[42:43], v[38:39] op_sel:[1,0]
	s_nop 0
	v_pk_mul_f32 v[38:39], v[38:39], v[36:37] op_sel:[0,1] op_sel_hi:[1,0]
	s_nop 0
	v_pk_fma_f32 v[32:33], v[32:33], v[36:37], v[38:39]
	ds_read_b128 v[36:39], v48
	ds_read_b128 v[40:43], v49
	v_pk_add_f32 v[4:5], v[4:5], v[32:33]
	v_and_b32_e32 v33, 0xffff0000, v34
	v_lshlrev_b32_e32 v32, 16, v34
	s_waitcnt lgkmcnt(1)
	v_mov_b32_e32 v45, v37
	s_waitcnt lgkmcnt(0)
	v_pk_mov_b32 v[36:37], v[40:41], v[36:37] op_sel:[1,0]
	v_mov_b32_e32 v44, v40
	v_pk_mul_f32 v[36:37], v[36:37], v[32:33] op_sel:[0,1] op_sel_hi:[1,0]
	v_mov_b32_e32 v34, v42
	v_pk_fma_f32 v[32:33], v[44:45], v[32:33], v[36:37]
	v_pk_mov_b32 v[36:37], v[42:43], v[38:39] op_sel:[1,0]
	v_pk_add_f32 v[4:5], v[4:5], v[32:33]
	v_and_b32_e32 v33, 0xffff0000, v35
	v_lshlrev_b32_e32 v32, 16, v35
	v_mov_b32_e32 v35, v39
	v_pk_mul_f32 v[36:37], v[36:37], v[32:33] op_sel:[0,1] op_sel_hi:[1,0]
	v_and_b32_e32 v41, 0xffff0000, v28
	v_pk_fma_f32 v[32:33], v[34:35], v[32:33], v[36:37]
	v_add_u32_e32 v36, 0x12040, v52
	v_pk_add_f32 v[4:5], v[4:5], v[32:33]
	v_add_u32_e32 v32, 0x11840, v52
	ds_read_b128 v[32:35], v32
	ds_read_b128 v[36:39], v36
	v_lshlrev_b32_e32 v40, 16, v28
	v_add_u32_e32 v44, 0x11850, v52
	v_add_u32_e32 v45, 0x12050, v52
	s_waitcnt lgkmcnt(1)
	v_mov_b32_e32 v43, v33
	s_waitcnt lgkmcnt(0)
	v_pk_mov_b32 v[32:33], v[36:37], v[32:33] op_sel:[1,0]
	v_mov_b32_e32 v42, v36
	v_pk_mul_f32 v[32:33], v[32:33], v[40:41] op_sel:[0,1] op_sel_hi:[1,0]
	v_mov_b32_e32 v28, v38
	v_pk_fma_f32 v[32:33], v[42:43], v[40:41], v[32:33]
	s_nop 0
	v_pk_add_f32 v[4:5], v[4:5], v[32:33]
	v_and_b32_e32 v33, 0xffff0000, v29
	v_lshlrev_b32_e32 v32, 16, v29
	v_mov_b32_e32 v29, v35
	v_pk_mov_b32 v[34:35], v[38:39], v[34:35] op_sel:[1,0]
	s_nop 0
	v_pk_mul_f32 v[34:35], v[34:35], v[32:33] op_sel:[0,1] op_sel_hi:[1,0]
	s_nop 0
	v_pk_fma_f32 v[28:29], v[28:29], v[32:33], v[34:35]
	ds_read_b128 v[32:35], v44
	ds_read_b128 v[36:39], v45
	v_pk_add_f32 v[4:5], v[4:5], v[28:29]
	v_and_b32_e32 v29, 0xffff0000, v30
	v_lshlrev_b32_e32 v28, 16, v30
	s_waitcnt lgkmcnt(1)
	v_mov_b32_e32 v41, v33
	s_waitcnt lgkmcnt(0)
	v_pk_mov_b32 v[32:33], v[36:37], v[32:33] op_sel:[1,0]
	v_mov_b32_e32 v40, v36
	v_pk_mul_f32 v[32:33], v[32:33], v[28:29] op_sel:[0,1] op_sel_hi:[1,0]
	v_mov_b32_e32 v30, v38
	v_pk_fma_f32 v[28:29], v[40:41], v[28:29], v[32:33]
	v_pk_mov_b32 v[32:33], v[38:39], v[34:35] op_sel:[1,0]
	v_pk_add_f32 v[4:5], v[4:5], v[28:29]
	v_and_b32_e32 v29, 0xffff0000, v31
	v_lshlrev_b32_e32 v28, 16, v31
	v_mov_b32_e32 v31, v35
	v_pk_mul_f32 v[32:33], v[32:33], v[28:29] op_sel:[0,1] op_sel_hi:[1,0]
	v_and_b32_e32 v37, 0xffff0000, v24
	v_pk_fma_f32 v[28:29], v[30:31], v[28:29], v[32:33]
	v_add_u32_e32 v32, 0x12060, v52
	v_pk_add_f32 v[4:5], v[4:5], v[28:29]
	v_add_u32_e32 v28, 0x11860, v52
	ds_read_b128 v[28:31], v28
	ds_read_b128 v[32:35], v32
	v_lshlrev_b32_e32 v36, 16, v24
	v_add_u32_e32 v40, 0x11870, v52
	v_add_u32_e32 v41, 0x12070, v52
	s_waitcnt lgkmcnt(1)
	v_mov_b32_e32 v39, v29
	s_waitcnt lgkmcnt(0)
	v_pk_mov_b32 v[28:29], v[32:33], v[28:29] op_sel:[1,0]
	v_mov_b32_e32 v38, v32
	v_pk_mul_f32 v[28:29], v[28:29], v[36:37] op_sel:[0,1] op_sel_hi:[1,0]
	v_mov_b32_e32 v24, v34
	v_pk_fma_f32 v[28:29], v[38:39], v[36:37], v[28:29]
	s_nop 0
	v_pk_add_f32 v[4:5], v[4:5], v[28:29]
	v_and_b32_e32 v29, 0xffff0000, v25
	v_lshlrev_b32_e32 v28, 16, v25
	v_mov_b32_e32 v25, v31
	v_pk_mov_b32 v[30:31], v[34:35], v[30:31] op_sel:[1,0]
	s_nop 0
	v_pk_mul_f32 v[30:31], v[30:31], v[28:29] op_sel:[0,1] op_sel_hi:[1,0]
	s_nop 0
	v_pk_fma_f32 v[24:25], v[24:25], v[28:29], v[30:31]
	ds_read_b128 v[28:31], v40
	ds_read_b128 v[32:35], v41
	v_pk_add_f32 v[4:5], v[4:5], v[24:25]
	v_and_b32_e32 v25, 0xffff0000, v26
	v_lshlrev_b32_e32 v24, 16, v26
	s_waitcnt lgkmcnt(1)
	v_mov_b32_e32 v37, v29
	s_waitcnt lgkmcnt(0)
	v_pk_mov_b32 v[28:29], v[32:33], v[28:29] op_sel:[1,0]
	v_mov_b32_e32 v36, v32
	v_pk_mul_f32 v[28:29], v[28:29], v[24:25] op_sel:[0,1] op_sel_hi:[1,0]
	v_mov_b32_e32 v26, v34
	v_pk_fma_f32 v[24:25], v[36:37], v[24:25], v[28:29]
	v_pk_mov_b32 v[28:29], v[34:35], v[30:31] op_sel:[1,0]
	v_pk_add_f32 v[4:5], v[4:5], v[24:25]
	v_and_b32_e32 v25, 0xffff0000, v27
	v_lshlrev_b32_e32 v24, 16, v27
	v_mov_b32_e32 v27, v31
	v_pk_mul_f32 v[28:29], v[28:29], v[24:25] op_sel:[0,1] op_sel_hi:[1,0]
	s_nop 0
	v_pk_fma_f32 v[24:25], v[26:27], v[24:25], v[28:29]
	s_nop 0
	v_pk_add_f32 v[4:5], v[4:5], v[24:25]
	s_cbranch_scc1 .LBB0_892
	s_cmp_eq_u32 s52, 0
	s_cselect_b64 s[42:43], -1, 0
	s_cmp_gt_u32 s52, 1
	s_cselect_b64 s[46:47], -1, 0
	s_cmp_gt_u32 s52, 2
	v_cndmask_b32_e64 v6, v23, v188, s[42:43]
	v_cndmask_b32_e64 v7, v188, v22, s[46:47]
	s_cselect_b64 vcc, -1, 0
	v_cndmask_b32_e32 v8, v188, v21, vcc
	s_cmp_gt_u32 s52, 3
	v_cmp_gt_f32_e64 s[50:51], v7, v6
	s_cselect_b64 s[38:39], -1, 0
	s_cmp_gt_u32 s52, 4
	v_cndmask_b32_e64 v21, 0, 1, s[50:51]
	v_cmp_gt_f32_e64 s[50:51], v8, v6
	v_cndmask_b32_e64 v20, v188, v20, s[38:39]
	s_cselect_b64 s[40:41], -1, 0
	v_addc_co_u32_e64 v21, s[50:51], 0, v21, s[50:51]
	v_cndmask_b32_e64 v19, v188, v19, s[40:41]
	s_cmp_gt_u32 s52, 5
	v_cmp_gt_f32_e64 s[50:51], v20, v6
	s_cselect_b64 s[44:45], -1, 0
	s_cmp_eq_u32 s52, 7
	v_cndmask_b32_e64 v22, 0, 1, s[50:51]
	v_cmp_gt_f32_e64 s[50:51], v19, v6
	v_cndmask_b32_e64 v18, v188, v18, s[44:45]
	s_cselect_b64 s[48:49], -1, 0
	v_addc_co_u32_e64 v21, s[50:51], v21, v22, s[50:51]
	v_cndmask_b32_e64 v17, v188, v17, s[48:49]
	v_cmp_gt_f32_e64 s[50:51], v18, v6
	s_lshl_b32 s5, -1, s52
	v_lshlrev_b32_e32 v191, 2, v12
	v_cndmask_b32_e64 v22, 0, 1, s[50:51]
	v_cmp_gt_f32_e64 s[50:51], v17, v6
	s_lshl_b32 s17, s52, 2
	s_mov_b32 s85, 0
	v_addc_co_u32_e64 v21, s[50:51], v21, v22, s[50:51]
	v_cmp_gt_u32_e64 s[50:51], 3, v21
	s_or_b32 s16, s4, 31
	v_add_u32_e32 v179, 14, v149
	v_cndmask_b32_e64 v21, 0, 1, s[50:51]
	v_cmp_ge_f32_e64 s[50:51], v6, v7
	v_add_u32_e32 v178, 13, v149
	v_mov_b32_e32 v177, 0
	v_cndmask_b32_e64 v22, 0, 1, s[50:51]
	v_cmp_gt_f32_e64 s[50:51], v8, v7
	v_mov_b32_e32 v181, 0xf149f2ca
	s_nop 0
	v_addc_co_u32_e64 v22, s[50:51], 0, v22, s[50:51]
	v_cmp_gt_f32_e64 s[50:51], v20, v7
	s_nop 1
	v_cndmask_b32_e64 v23, 0, 1, s[50:51]
	v_cmp_gt_f32_e64 s[50:51], v19, v7
	s_nop 1
	v_addc_co_u32_e64 v22, s[50:51], v22, v23, s[50:51]
	v_cmp_gt_f32_e64 s[50:51], v18, v7
	s_nop 1
	v_cndmask_b32_e64 v23, 0, 1, s[50:51]
	v_cmp_gt_f32_e64 s[50:51], v17, v7
	s_nop 1
	v_addc_co_u32_e64 v22, s[50:51], v22, v23, s[50:51]
	v_cmp_lt_u32_e64 s[50:51], 2, v22
	s_nop 1
	v_cndmask_b32_e64 v22, 2, 0, s[50:51]
	v_cmp_ge_f32_e64 s[50:51], v7, v8
	v_or_b32_e32 v21, v22, v21
	s_nop 0
	v_cndmask_b32_e64 v22, 0, 1, s[50:51]
	v_cmp_ge_f32_e64 s[50:51], v6, v8
	s_nop 1
	v_addc_co_u32_e64 v22, s[50:51], 0, v22, s[50:51]
	v_cmp_gt_f32_e64 s[50:51], v20, v8
	s_nop 1
	v_cndmask_b32_e64 v23, 0, 1, s[50:51]
	v_cmp_gt_f32_e64 s[50:51], v19, v8
	s_nop 1
	v_addc_co_u32_e64 v22, s[50:51], v22, v23, s[50:51]
	v_cmp_gt_f32_e64 s[50:51], v18, v8
	s_nop 1
	v_cndmask_b32_e64 v23, 0, 1, s[50:51]
	v_cmp_gt_f32_e64 s[50:51], v17, v8
	s_nop 1
	v_addc_co_u32_e64 v22, s[50:51], v22, v23, s[50:51]
	v_cmp_gt_u32_e64 s[50:51], 3, v22
	s_nop 1
	v_cndmask_b32_e64 v22, 0, 4, s[50:51]
	v_cmp_ge_f32_e64 s[50:51], v7, v20
	s_nop 1
	v_cndmask_b32_e64 v23, 0, 1, s[50:51]
	v_cmp_ge_f32_e64 s[50:51], v6, v20
	s_nop 1
	v_addc_co_u32_e64 v23, s[50:51], 0, v23, s[50:51]
	v_cmp_ge_f32_e64 s[50:51], v8, v20
	s_nop 1
	v_cndmask_b32_e64 v24, 0, 1, s[50:51]
	v_cmp_gt_f32_e64 s[50:51], v19, v20
	s_nop 1
	v_addc_co_u32_e64 v23, s[50:51], v23, v24, s[50:51]
	v_cmp_gt_f32_e64 s[50:51], v18, v20
	s_nop 1
	v_cndmask_b32_e64 v24, 0, 1, s[50:51]
	v_cmp_gt_f32_e64 s[50:51], v17, v20
	s_nop 1
	v_addc_co_u32_e64 v23, s[50:51], v23, v24, s[50:51]
	v_cmp_gt_u32_e64 s[50:51], 3, v23
	s_nop 1
	v_cndmask_b32_e64 v23, 0, 8, s[50:51]
	v_cmp_ge_f32_e64 s[50:51], v7, v19
	v_or3_b32 v21, v21, v22, v23
	s_nop 0
	v_cndmask_b32_e64 v22, 0, 1, s[50:51]
	v_cmp_ge_f32_e64 s[50:51], v6, v19
	s_nop 1
	v_addc_co_u32_e64 v22, s[50:51], 0, v22, s[50:51]
	v_cmp_ge_f32_e64 s[50:51], v8, v19
	s_nop 1
	v_cndmask_b32_e64 v23, 0, 1, s[50:51]
	v_cmp_ge_f32_e64 s[50:51], v20, v19
	s_nop 1
	v_addc_co_u32_e64 v22, s[50:51], v22, v23, s[50:51]
	v_cmp_gt_f32_e64 s[50:51], v18, v19
	s_nop 1
	v_cndmask_b32_e64 v23, 0, 1, s[50:51]
	v_cmp_gt_f32_e64 s[50:51], v17, v19
	s_nop 1
	v_addc_co_u32_e64 v22, s[50:51], v22, v23, s[50:51]
	v_cmp_gt_u32_e64 s[50:51], 3, v22
	s_nop 1
	v_cndmask_b32_e64 v22, 0, 16, s[50:51]
	v_cmp_ge_f32_e64 s[50:51], v7, v18
	s_nop 1
	v_cndmask_b32_e64 v23, 0, 1, s[50:51]
	v_cmp_ge_f32_e64 s[50:51], v6, v18
	s_nop 1
	v_addc_co_u32_e64 v23, s[50:51], 0, v23, s[50:51]
	v_cmp_ge_f32_e64 s[50:51], v8, v18
	s_nop 1
	v_cndmask_b32_e64 v24, 0, 1, s[50:51]
	v_cmp_ge_f32_e64 s[50:51], v20, v18
	s_nop 1
	v_addc_co_u32_e64 v23, s[50:51], v23, v24, s[50:51]
	v_cmp_ge_f32_e64 s[50:51], v19, v18
	s_nop 1
	v_cndmask_b32_e64 v24, 0, 1, s[50:51]
	v_cmp_gt_f32_e64 s[50:51], v17, v18
	s_nop 1
	v_addc_co_u32_e64 v23, s[50:51], v23, v24, s[50:51]
	v_cmp_gt_u32_e64 s[50:51], 3, v23
	s_nop 1
	v_cndmask_b32_e64 v23, 0, 32, s[50:51]
	v_cmp_ge_f32_e64 s[50:51], v7, v17
	v_or3_b32 v21, v21, v22, v23
	s_nop 0
	v_cndmask_b32_e64 v7, 0, 1, s[50:51]
	v_cmp_ge_f32_e64 s[50:51], v6, v17
	s_nop 1
	v_addc_co_u32_e64 v6, s[50:51], 0, v7, s[50:51]
	v_cmp_ge_f32_e64 s[50:51], v8, v17
	ds_bpermute_b32 v8, v14, v5
	s_waitcnt lgkmcnt(0)
	v_cndmask_b32_e64 v23, v188, v8, s[46:47]
	v_cndmask_b32_e64 v7, 0, 1, s[50:51]
	v_cmp_ge_f32_e64 s[50:51], v20, v17
	ds_bpermute_b32 v8, v14, v4
	s_waitcnt lgkmcnt(0)
	v_cndmask_b32_e64 v27, v188, v8, s[44:45]
	v_addc_co_u32_e64 v6, s[50:51], v6, v7, s[50:51]
	v_cmp_ge_f32_e64 s[50:51], v19, v17
	v_lshlrev_b32_e32 v8, 4, v12
	s_nop 0
	v_cndmask_b32_e64 v7, 0, 1, s[50:51]
	v_cmp_ge_f32_e64 s[50:51], v18, v17
	s_nop 1
	v_addc_co_u32_e64 v6, s[50:51], v6, v7, s[50:51]
	ds_bpermute_b32 v7, v13, v5
	v_cmp_gt_u32_e64 s[50:51], 3, v6
	s_waitcnt lgkmcnt(0)
	v_cndmask_b32_e64 v22, v7, v188, s[42:43]
	v_cndmask_b32_e64 v6, 0, 64, s[50:51]
	v_or_b32_e32 v24, v21, v6
	v_bitop3_b32 v190, v21, s5, v6 bitop3:0x32
	ds_bpermute_b32 v6, v15, v5
	ds_bpermute_b32 v7, v13, v4
	ds_bpermute_b32 v4, v15, v4
	ds_bpermute_b32 v5, v16, v5
	s_waitcnt lgkmcnt(3)
	v_cndmask_b32_e32 v13, v188, v6, vcc
	v_cmp_gt_f32_e32 vcc, v23, v22
	s_waitcnt lgkmcnt(1)
	v_cndmask_b32_e64 v28, v188, v4, s[48:49]
	s_waitcnt lgkmcnt(0)
	v_cndmask_b32_e64 v25, v188, v5, s[38:39]
	v_cndmask_b32_e64 v4, 0, 1, vcc
	v_cmp_gt_f32_e32 vcc, v13, v22
	v_cndmask_b32_e64 v26, v188, v7, s[40:41]
	s_nop 0
	v_addc_co_u32_e32 v4, vcc, 0, v4, vcc
	v_cmp_gt_f32_e32 vcc, v25, v22
	s_nop 1
	v_cndmask_b32_e64 v5, 0, 1, vcc
	v_cmp_gt_f32_e32 vcc, v26, v22
	s_nop 1
	v_addc_co_u32_e32 v4, vcc, v4, v5, vcc
	v_cmp_gt_f32_e32 vcc, v27, v22
	s_nop 1
	v_cndmask_b32_e64 v5, 0, 1, vcc
	v_cmp_gt_f32_e32 vcc, v28, v22
	s_nop 1
	v_addc_co_u32_e32 v4, vcc, v4, v5, vcc
	v_cmp_gt_u32_e32 vcc, 3, v4
	s_nop 1
	v_cndmask_b32_e64 v4, 0, 1, vcc
	v_cmp_ge_f32_e32 vcc, v22, v23
	s_nop 1
	v_cndmask_b32_e64 v5, 0, 1, vcc
	v_cmp_gt_f32_e32 vcc, v13, v23
	s_nop 1
	v_addc_co_u32_e32 v5, vcc, 0, v5, vcc
	v_cmp_gt_f32_e32 vcc, v25, v23
	s_nop 1
	v_cndmask_b32_e64 v6, 0, 1, vcc
	v_cmp_gt_f32_e32 vcc, v26, v23
	s_nop 1
	v_addc_co_u32_e32 v5, vcc, v5, v6, vcc
	v_cmp_gt_f32_e32 vcc, v27, v23
	s_nop 1
	v_cndmask_b32_e64 v6, 0, 1, vcc
	v_cmp_gt_f32_e32 vcc, v28, v23
	s_nop 1
	v_addc_co_u32_e32 v5, vcc, v5, v6, vcc
	v_cmp_lt_u32_e32 vcc, 2, v5
	v_mov_b32_e32 v6, v170
	s_nop 0
	v_cndmask_b32_e64 v5, 2, 0, vcc
	v_cmp_ge_f32_e32 vcc, v23, v13
	v_or_b32_e32 v29, v5, v4
	s_nop 0
	v_cndmask_b32_e64 v4, 0, 1, vcc
	v_cmp_ge_f32_e32 vcc, v22, v13
	s_nop 1
	v_addc_co_u32_e32 v4, vcc, 0, v4, vcc
	v_cmp_gt_f32_e32 vcc, v25, v13
	s_nop 1
	v_cndmask_b32_e64 v5, 0, 1, vcc
	v_cmp_gt_f32_e32 vcc, v26, v13
	s_nop 1
	v_addc_co_u32_e32 v4, vcc, v4, v5, vcc
	v_cmp_gt_f32_e32 vcc, v27, v13
	s_nop 1
	v_cndmask_b32_e64 v5, 0, 1, vcc
	v_cmp_gt_f32_e32 vcc, v28, v13
	s_nop 1
	v_addc_co_u32_e32 v4, vcc, v4, v5, vcc
	v_cmp_gt_u32_e32 vcc, 3, v4
	s_nop 1
	v_cndmask_b32_e64 v30, 0, 4, vcc
	v_cmp_ge_f32_e32 vcc, v23, v25
	s_nop 1
	v_cndmask_b32_e64 v4, 0, 1, vcc
	v_cmp_ge_f32_e32 vcc, v22, v25
	s_nop 1
	v_addc_co_u32_e32 v4, vcc, 0, v4, vcc
	v_cmp_ge_f32_e32 vcc, v13, v25
	s_nop 1
	v_cndmask_b32_e64 v5, 0, 1, vcc
	v_cmp_gt_f32_e32 vcc, v26, v25
	s_nop 1
	v_addc_co_u32_e32 v31, vcc, v4, v5, vcc
	v_lshl_add_u64 v[4:5], s[22:23], 0, v[8:9]
	v_lshl_add_u64 v[0:1], v[4:5], 0, v[0:1]
	global_load_dwordx4 v[92:95], v[0:1], off
	global_load_dwordx4 v[84:87], v[0:1], off offset:64
	global_load_dwordx4 v[76:79], v[0:1], off offset:128
	global_load_dwordx4 v[68:71], v[0:1], off offset:192
	v_lshl_add_u64 v[0:1], v[4:5], 0, v[2:3]
	global_load_dwordx4 v[96:99], v[0:1], off
	global_load_dwordx4 v[88:91], v[0:1], off offset:64
	global_load_dwordx4 v[80:83], v[0:1], off offset:128
	global_load_dwordx4 v[72:75], v[0:1], off offset:192
	v_cmp_gt_f32_e32 vcc, v27, v25
	v_lshlrev_b32_e32 v0, 4, v6
	v_and_b32_e32 v8, 0xf0, v0
	v_lshrrev_b32_e32 v0, 4, v6
	v_lshl_add_u64 v[4:5], s[24:25], 0, v[8:9]
	v_add_u32_e32 v14, s9, v0
	v_mad_u64_u32 v[0:1], s[6:7], v14, s65, v[4:5]
	v_add_u32_e32 v6, 0x200, v6
	global_load_dwordx4 v[0:3], v[0:1], off
	v_lshrrev_b32_e32 v6, 4, v6
	v_add_u32_e32 v20, s9, v6
	v_mad_u64_u32 v[4:5], s[6:7], v20, s65, v[4:5]
	v_lshl_add_u64 v[18:19], s[26:27], 0, v[8:9]
	global_load_dwordx4 v[4:7], v[4:5], off
	v_mad_u64_u32 v[14:15], s[6:7], v14, s65, v[18:19]
	global_load_dwordx4 v[14:17], v[14:15], off
	v_mad_u64_u32 v[18:19], s[6:7], v20, s65, v[18:19]
	global_load_dwordx4 v[18:21], v[18:19], off
	v_cndmask_b32_e64 v32, 0, 1, vcc
	v_cmp_gt_f32_e32 vcc, v28, v25
	s_nop 1
	v_addc_co_u32_e32 v8, vcc, v31, v32, vcc
	v_cmp_gt_u32_e32 vcc, 3, v8
	s_nop 1
	v_cndmask_b32_e64 v8, 0, 8, vcc
	v_cmp_ge_f32_e32 vcc, v23, v26
	v_or3_b32 v8, v29, v30, v8
	s_nop 0
	v_cndmask_b32_e64 v29, 0, 1, vcc
	v_cmp_ge_f32_e32 vcc, v22, v26
	s_nop 1
	v_addc_co_u32_e32 v29, vcc, 0, v29, vcc
	v_cmp_ge_f32_e32 vcc, v13, v26
	s_nop 1
	v_cndmask_b32_e64 v30, 0, 1, vcc
	v_cmp_ge_f32_e32 vcc, v25, v26
	s_nop 1
	v_addc_co_u32_e32 v29, vcc, v29, v30, vcc
	v_cmp_gt_f32_e32 vcc, v27, v26
	s_nop 1
	v_cndmask_b32_e64 v30, 0, 1, vcc
	v_cmp_gt_f32_e32 vcc, v28, v26
	s_nop 1
	v_addc_co_u32_e32 v29, vcc, v29, v30, vcc
	v_cmp_gt_u32_e32 vcc, 3, v29
	s_nop 1
	v_cndmask_b32_e64 v29, 0, 16, vcc
	v_cmp_ge_f32_e32 vcc, v23, v27
	s_nop 1
	v_cndmask_b32_e64 v30, 0, 1, vcc
	v_cmp_ge_f32_e32 vcc, v22, v27
	s_nop 1
	v_addc_co_u32_e32 v30, vcc, 0, v30, vcc
	v_cmp_ge_f32_e32 vcc, v13, v27
	s_nop 1
	v_cndmask_b32_e64 v31, 0, 1, vcc
	v_cmp_ge_f32_e32 vcc, v25, v27
	s_nop 1
	v_addc_co_u32_e32 v30, vcc, v30, v31, vcc
	v_cmp_ge_f32_e32 vcc, v26, v27
	s_nop 1
	v_cndmask_b32_e64 v31, 0, 1, vcc
	v_cmp_gt_f32_e32 vcc, v28, v27
	s_nop 1
	v_addc_co_u32_e32 v30, vcc, v30, v31, vcc
	v_cmp_gt_u32_e32 vcc, 3, v30
	s_nop 1
	v_cndmask_b32_e64 v30, 0, 32, vcc
	v_cmp_ge_f32_e32 vcc, v23, v28
	v_or3_b32 v8, v8, v29, v30
	s_nop 0
	v_cndmask_b32_e64 v23, 0, 1, vcc
	v_cmp_ge_f32_e32 vcc, v22, v28
	s_nop 1
	v_addc_co_u32_e32 v22, vcc, 0, v23, vcc
	v_cmp_ge_f32_e32 vcc, v13, v28
	s_nop 1
	v_cndmask_b32_e64 v13, 0, 1, vcc
	v_cmp_ge_f32_e32 vcc, v25, v28
	s_nop 1
	v_addc_co_u32_e32 v13, vcc, v22, v13, vcc
	v_cmp_ge_f32_e32 vcc, v26, v28
	s_nop 1
	v_cndmask_b32_e64 v22, 0, 1, vcc
	v_cmp_ge_f32_e32 vcc, v27, v28
	s_nop 1
	v_addc_co_u32_e32 v13, vcc, v13, v22, vcc
	v_cmp_gt_u32_e32 vcc, 3, v13
	s_nop 1
	v_cndmask_b32_e64 v13, 0, 64, vcc
	v_or_b32_e32 v25, v8, v13
	v_bitop3_b32 v180, v8, s5, v13 bitop3:0x32
	v_mov_b32_e32 v13, v170
	v_bitop3_b32 v193, v25, v24, s5 bitop3:0x54
	v_lshlrev_b32_e32 v8, 4, v13
	v_and_b32_e32 v8, 0xf0, v8
	v_add_u32_e32 v8, 0, v8
	v_lshrrev_b32_e32 v26, 4, v13
	v_and_b32_e32 v248, 0xf0, v13
	v_xor_b32_e32 v248, v248, v8
	v_mov_b32_e32 v249, 0
	v_mad_u64_u32 v[22:23], s[6:7], v26, s33, v[248:249]
	s_waitcnt vmcnt(3)
	ds_write_b128 v22, v[0:3]
	v_add_u32_e32 v0, 0x200, v13
	v_lshrrev_b32_e32 v2, 4, v0
	v_mad_u64_u32 v[0:1], s[6:7], v2, s33, v[248:249]
	s_waitcnt vmcnt(2)
	ds_write_b128 v0, v[4:7]
	v_and_b32_e32 v22, 7, v26
	v_lshlrev_b32_e32 v22, 5, v22
	v_xor_b32_e32 v8, v8, v22
	v_mad_u64_u32 v[0:1], s[6:7], v26, s33, v[8:9]
	s_waitcnt vmcnt(1)
	ds_write_b128 v0, v[14:17] offset:34816
	v_mad_u64_u32 v[0:1], s[6:7], v2, s33, v[8:9]
	s_waitcnt vmcnt(0)
	ds_write_b128 v0, v[18:21] offset:34816
	v_lshlrev_b32_e32 v0, 8, v11
	v_and_b32_e32 v1, 48, v10
	v_lshlrev_b32_e32 v248, 4, v11
	v_xor_b32_e32 v1, v1, v248
	v_add3_u32 v192, 0, v0, v1
	v_lshrrev_b32_e32 v0, 2, v11
	v_or_b32_e32 v0, v191, v0
	v_lshlrev_b32_e32 v1, 3, v10
	v_and_b32_e32 v248, 7, v0
	v_lshlrev_b32_e32 v248, 5, v248
	v_lshl_or_b32 v0, v0, 8, v248
	v_and_b32_e32 v1, 24, v1
	v_add3_u32 v176, 0, v0, v1
	v_and_b32_e32 v1, 64, v184
	v_xor_b32_e32 v0, 16, v184
	v_add_u32_e32 v1, 64, v1
	v_cmp_lt_i32_e32 vcc, v0, v1
	v_mov_b32_e32 v8, v9
	v_mov_b32_e32 v10, v9
	v_cndmask_b32_e32 v0, v184, v0, vcc
	v_lshlrev_b32_e32 v175, 2, v0
	v_xor_b32_e32 v0, 32, v184
	v_cmp_lt_i32_e32 vcc, v0, v1
	v_mov_b32_e32 v11, v9
	v_mov_b64_e32 v[18:19], v[10:11]
	v_cndmask_b32_e32 v0, v184, v0, vcc
	v_lshlrev_b32_e32 v174, 2, v0
	v_mov_b64_e32 v[0:1], v[8:9]
	v_mov_b64_e32 v[26:27], v[10:11]
	v_mov_b64_e32 v[34:35], v[10:11]
	v_mov_b64_e32 v[14:15], v[10:11]
	v_mov_b64_e32 v[4:5], v[8:9]
	v_mov_b64_e32 v[22:23], v[10:11]
	v_mov_b64_e32 v[30:31], v[10:11]
	v_mov_b64_e32 v[38:39], v[10:11]
	v_mov_b64_e32 v[42:43], v[10:11]
	v_mov_b64_e32 v[46:47], v[10:11]
	v_mov_b64_e32 v[50:51], v[10:11]
	v_mov_b64_e32 v[54:55], v[10:11]
	v_mov_b64_e32 v[58:59], v[10:11]
	v_mov_b64_e32 v[62:63], v[10:11]
	v_mov_b64_e32 v[66:67], v[10:11]
	s_or_b32 s6, s17, 2
	v_mov_b64_e32 v[2:3], v[10:11]
	v_mov_b64_e32 v[16:17], v[8:9]
	v_mov_b64_e32 v[24:25], v[8:9]
	v_mov_b64_e32 v[32:33], v[8:9]
	v_mov_b64_e32 v[12:13], v[8:9]
	v_mov_b64_e32 v[6:7], v[10:11]
	v_mov_b64_e32 v[20:21], v[8:9]
	v_mov_b64_e32 v[28:29], v[8:9]
	v_mov_b64_e32 v[36:37], v[8:9]
	v_mov_b64_e32 v[40:41], v[8:9]
	v_mov_b64_e32 v[44:45], v[8:9]
	v_mov_b64_e32 v[48:49], v[8:9]
	v_mov_b64_e32 v[52:53], v[8:9]
	v_mov_b64_e32 v[56:57], v[8:9]
	v_mov_b64_e32 v[60:61], v[8:9]
	v_mov_b64_e32 v[64:65], v[8:9]
	v_mov_b32_e32 v11, 0xf149f2ca
	v_mov_b32_e32 v10, 0
	s_mov_b32 s7, 0
	v_lshrrev_b32_e32 v108, 4, v170
	v_and_b32_e32 v109, 15, v170
	v_and_b32_e32 v110, 15, v108
	v_xor_b32_e32 v110, v109, v110
	v_and_b32_e32 v111, 7, v108
	v_lshlrev_b32_e32 v111, 1, v111
	v_xor_b32_e32 v109, v109, v111
	v_mul_u32_u24_e32 v111, 0x3000, v108
	v_lshl_or_b32 v108, v110, 4, v111
	v_lshl_or_b32 v109, v109, 4, v111
	s_waitcnt lgkmcnt(0)
	s_barrier
.LBB0_894:
	v_sub_co_u32_e64 v116, s[38:39], s7, 4
	s_xor_b64 s[4:5], s[38:39], -1
	s_add_i32 s44, s9, s85
	s_cmp_gt_u32 s7, 2
	s_cselect_b64 s[36:37], -1, 0
	s_add_i32 s45, s44, 64
	s_add_i32 s46, s85, 0xffffff40
	s_cmp_lt_u32 s7, 3
	s_cselect_b64 s[62:63], -1, 0
	s_and_b64 s[42:43], s[62:63], exec
	s_cselect_b32 s45, s45, s46
	s_mul_i32 s42, s45, 0x3000
	s_add_i32 s43, s42, 0x60000
	v_add_u32_e32 v100, s42, v108
	v_add_u32_e32 v101, s43, v108
	v_add_u32_e32 v112, s42, v109
	v_add_u32_e32 v113, s43, v109
	s_and_b32 s86, s7, 1
	s_cselect_b32 m0, 0, 0x4400
	v_readlane_b32 s43, v254, 60
	s_lshl_b32 s43, s43, 10
	s_add_i32 m0, m0, s43
	v_ashrrev_i32_e32 v8, 2, v116
	global_load_lds_dwordx4 v100, s[24:25]
	s_add_i32 m0, m0, 0x2000
	s_mov_b64 s[40:41], -1
	global_load_lds_dwordx4 v101, s[24:25]
	s_cmp_eq_u32 s86, 0
	s_cselect_b32 m0, 0x4800, 0
	s_add_i32 m0, m0, s43
	s_add_i32 m0, m0, 0x8800
	s_nop 0
	global_load_lds_dwordx4 v112, s[26:27]
	s_add_i32 m0, m0, 0x2000
	s_nop 0
	global_load_lds_dwordx4 v113, s[26:27]
	v_lshlrev_b32_e64 v8, v8, 1
	s_and_b64 vcc, exec, s[4:5]
	s_cbranch_vccz .LBB0_897
	v_and_b32_e32 v116, v8, v193
	v_cmp_ne_u32_e32 vcc, 0, v116
	s_cmp_lg_u64 vcc, 0
	s_cselect_b64 s[42:43], -1, 0
	s_cbranch_execz .LBB0_898

.LBB0_911:
	s_waitcnt lgkmcnt(0)
	v_max3_f32 v8, v11, v221, v222
	v_sub_f32_e32 v116, v208, v8
	v_exp_f32_e32 v116, v116
	v_sub_f32_e32 v117, v204, v8
	v_exp_f32_e32 v117, v117
	v_sub_f32_e32 v118, v200, v8
	v_exp_f32_e32 v118, v118
	v_sub_f32_e32 v119, v195, v8
	v_exp_f32_e32 v119, v119
	v_add_f32_e32 v120, 0, v116
	v_add_f32_e32 v120, v117, v120
	v_add_f32_e32 v120, v118, v120
	v_add_f32_e32 v122, v119, v120
	v_cvt_pk_bf16_f32 v120, v116, v117
	v_sub_f32_e32 v116, v207, v8
	v_exp_f32_e32 v116, v116
	v_sub_f32_e32 v117, v203, v8
	v_cvt_pk_bf16_f32 v121, v118, v119
	v_exp_f32_e32 v117, v117
	v_sub_f32_e32 v118, v199, v8
	v_exp_f32_e32 v118, v118
	v_sub_f32_e32 v119, v196, v8
	v_exp_f32_e32 v119, v119
	v_add_f32_e32 v122, v116, v122
	v_add_f32_e32 v122, v117, v122
	v_add_f32_e32 v122, v118, v122
	v_add_f32_e32 v124, v119, v122
	v_cvt_pk_bf16_f32 v122, v116, v117
	v_sub_f32_e32 v116, v206, v8
	v_exp_f32_e32 v116, v116
	v_sub_f32_e32 v117, v202, v8
	v_cvt_pk_bf16_f32 v123, v118, v119
	v_exp_f32_e32 v117, v117
	v_add_f32_e32 v118, v116, v124
	v_sub_f32_e32 v119, v197, v8
	v_sub_f32_e32 v124, v194, v8
	v_exp_f32_e32 v119, v119
	v_exp_f32_e32 v124, v124
	v_add_f32_e32 v118, v117, v118
	v_sub_f32_e32 v125, v209, v8
	v_add_f32_e32 v118, v119, v118
	v_exp_f32_e32 v125, v125
	v_cvt_pk_bf16_f32 v116, v116, v117
	v_cvt_pk_bf16_f32 v117, v119, v124
	v_sub_f32_e32 v119, v205, v8
	v_add_f32_e32 v118, v124, v118
	v_exp_f32_e32 v119, v119
	v_sub_f32_e32 v124, v201, v8
	v_exp_f32_e32 v126, v124
	v_sub_f32_e32 v124, v198, v8
	v_sub_f32_e32 v11, v11, v8
	v_exp_f32_e32 v127, v124
	v_add_f32_e32 v118, v125, v118
	v_exp_f32_e32 v124, v11
	v_add_f32_e32 v118, v119, v118
	v_add_f32_e32 v118, v126, v118
	v_add_f32_e32 v154, v127, v118
	v_fmac_f32_e32 v154, v10, v124
	v_cvt_pk_bf16_f32 v118, v125, v119
	v_pk_mul_f32 v[66:67], v[66:67], v[124:125] op_sel_hi:[1,0]
	v_pk_mul_f32 v[64:65], v[64:65], v[124:125] op_sel_hi:[1,0]
	v_pk_mul_f32 v[62:63], v[62:63], v[124:125] op_sel_hi:[1,0]
	v_pk_mul_f32 v[60:61], v[60:61], v[124:125] op_sel_hi:[1,0]
	v_pk_mul_f32 v[58:59], v[58:59], v[124:125] op_sel_hi:[1,0]
	v_pk_mul_f32 v[56:57], v[56:57], v[124:125] op_sel_hi:[1,0]
	v_pk_mul_f32 v[54:55], v[54:55], v[124:125] op_sel_hi:[1,0]
	v_pk_mul_f32 v[52:53], v[52:53], v[124:125] op_sel_hi:[1,0]
	v_max3_f32 v10, v132, v133, v135
	v_cvt_pk_bf16_f32 v119, v126, v127
	v_max3_f32 v11, v140, v142, v145
	v_max3_f32 v10, v10, v138, v134
	v_max3_f32 v11, v11, v141, v144
	v_max3_f32 v10, v10, v136, v139
	v_max3_f32 v11, v11, v146, v147
	v_max3_f32 v10, v10, v143, v137
	v_max3_f32 v10, v10, s3, v11
	ds_bpermute_b32 v11, v175, v10
	v_pk_mul_f32 v[50:51], v[50:51], v[124:125] op_sel_hi:[1,0]
	v_pk_mul_f32 v[48:49], v[48:49], v[124:125] op_sel_hi:[1,0]
	v_pk_mul_f32 v[46:47], v[46:47], v[124:125] op_sel_hi:[1,0]
	v_pk_mul_f32 v[44:45], v[44:45], v[124:125] op_sel_hi:[1,0]
	s_waitcnt lgkmcnt(0)
	v_max_f32_e32 v10, v10, v11
	ds_bpermute_b32 v11, v174, v10
	v_pk_mul_f32 v[42:43], v[42:43], v[124:125] op_sel_hi:[1,0]
	v_pk_mul_f32 v[40:41], v[40:41], v[124:125] op_sel_hi:[1,0]
	v_pk_mul_f32 v[38:39], v[38:39], v[124:125] op_sel_hi:[1,0]
	v_pk_mul_f32 v[36:37], v[36:37], v[124:125] op_sel_hi:[1,0]
	s_waitcnt lgkmcnt(0)
	v_max3_f32 v155, v181, v10, v11
	v_sub_f32_e32 v11, v138, v155
	v_exp_f32_e32 v11, v11
	v_sub_f32_e32 v124, v135, v155
	v_exp_f32_e32 v124, v124
	v_sub_f32_e32 v125, v133, v155
	v_exp_f32_e32 v125, v125
	v_sub_f32_e32 v126, v132, v155
	v_exp_f32_e32 v126, v126
	v_add_f32_e32 v127, 0, v11
	v_add_f32_e32 v127, v124, v127
	v_cvt_pk_bf16_f32 v128, v11, v124
	v_sub_f32_e32 v11, v143, v155
	v_sub_f32_e32 v124, v139, v155
	v_add_f32_e32 v127, v125, v127
	v_exp_f32_e32 v11, v11
	v_exp_f32_e32 v124, v124
	v_add_f32_e32 v127, v126, v127
	v_cvt_pk_bf16_f32 v129, v125, v126
	v_sub_f32_e32 v125, v136, v155
	v_sub_f32_e32 v126, v134, v155
	v_exp_f32_e32 v125, v125
	v_exp_f32_e32 v126, v126
	v_add_f32_e32 v127, v11, v127
	v_cvt_pk_bf16_f32 v130, v11, v124
	v_sub_f32_e32 v11, v145, v155
	v_add_f32_e32 v127, v124, v127
	v_exp_f32_e32 v11, v11
	v_sub_f32_e32 v124, v142, v155
	v_add_f32_e32 v127, v125, v127
	v_cvt_pk_bf16_f32 v131, v125, v126
	v_exp_f32_e32 v124, v124
	v_sub_f32_e32 v125, v140, v155
	v_add_f32_e32 v127, v126, v127
	v_exp_f32_e32 v125, v125
	v_sub_f32_e32 v126, v137, v155
	v_exp_f32_e32 v126, v126
	v_add_f32_e32 v127, v11, v127
	v_add_f32_e32 v127, v124, v127
	v_add_f32_e32 v127, v125, v127
	v_cvt_pk_bf16_f32 v124, v11, v124
	v_sub_f32_e32 v11, v147, v155
	v_add_f32_e32 v127, v126, v127
	v_cvt_pk_bf16_f32 v125, v125, v126
	v_exp_f32_e32 v11, v11
	v_sub_f32_e32 v126, v146, v155
	v_exp_f32_e32 v126, v126
	v_sub_f32_e32 v132, v144, v155
	v_exp_f32_e32 v132, v132
	v_sub_f32_e32 v133, v141, v155
	v_exp_f32_e32 v133, v133
	v_add_f32_e32 v127, v11, v127
	v_add_f32_e32 v127, v126, v127
	s_mul_i32 s4, s86, 0x4800
	v_sub_f32_e32 v10, v181, v155
	v_add_f32_e32 v127, v132, v127
	v_add_u32_e32 v157, s4, v176
	v_xor_b32_e32 v226, 0x20, v157
	v_xor_b32_e32 v227, 0x40, v157
	v_xor_b32_e32 v228, 0x60, v157
	v_xor_b32_e32 v229, 0x80, v157
	v_xor_b32_e32 v230, 0xa0, v157
	v_xor_b32_e32 v231, 0xc0, v157
	v_xor_b32_e32 v232, 0xe0, v157
	v_add_f32_e32 v156, v133, v127
	v_cvt_pk_bf16_f32 v127, v132, v133
	v_exp_f32_e32 v10, v10
	ds_read_b64_tr_b16 v[134:135], v157 offset:38912
	ds_read_b64_tr_b16 v[132:133], v157 offset:34816
	ds_read_b64_tr_b16 v[136:137], v226 offset:34816
	ds_read_b64_tr_b16 v[140:141], v227 offset:34816
	ds_read_b64_tr_b16 v[144:145], v228 offset:34816
	ds_read_b64_tr_b16 v[138:139], v226 offset:38912
	ds_read_b64_tr_b16 v[142:143], v227 offset:38912
	ds_read_b64_tr_b16 v[146:147], v228 offset:38912
	s_waitcnt lgkmcnt(6)
	v_mfma_f32_16x16x32_bf16 v[64:67], v[132:135], v[120:123], v[64:67]
	v_mul_f32_e64 v30, v30, v10
	v_mul_f32_e64 v31, v31, v10
	v_pk_mul_f32 v[28:29], v[28:29], v[10:11] op_sel_hi:[1,0]
	v_pk_mul_f32 v[22:23], v[22:23], v[10:11] op_sel_hi:[1,0]
	v_pk_mul_f32 v[20:21], v[20:21], v[10:11] op_sel_hi:[1,0]
	v_pk_mul_f32 v[6:7], v[6:7], v[10:11] op_sel_hi:[1,0]
	v_pk_mul_f32 v[4:5], v[4:5], v[10:11] op_sel_hi:[1,0]
	v_mfma_f32_16x16x32_bf16 v[28:31], v[132:135], v[128:131], v[28:31]
	v_mul_f32_e64 v14, v14, v10
	v_mul_f32_e64 v15, v15, v10
	v_pk_mul_f32 v[12:13], v[12:13], v[10:11] op_sel_hi:[1,0]
	v_cvt_pk_bf16_f32 v126, v11, v126
	s_waitcnt lgkmcnt(2)
	v_mfma_f32_16x16x32_bf16 v[60:63], v[136:139], v[120:123], v[60:63]
	v_fmac_f32_e32 v156, v177, v10
	v_pk_mul_f32 v[34:35], v[34:35], v[10:11] op_sel_hi:[1,0]
	v_pk_mul_f32 v[32:33], v[32:33], v[10:11] op_sel_hi:[1,0]
	v_mfma_f32_16x16x32_bf16 v[20:23], v[136:139], v[128:131], v[20:23]
	v_mul_f32_e64 v26, v26, v10
	v_mul_f32_e64 v27, v27, v10
	v_pk_mul_f32 v[24:25], v[24:25], v[10:11] op_sel_hi:[1,0]
	v_pk_mul_f32 v[18:19], v[18:19], v[10:11] op_sel_hi:[1,0]
	s_waitcnt lgkmcnt(1)
	v_mfma_f32_16x16x32_bf16 v[56:59], v[140:143], v[120:123], v[56:59]
	v_mul_f32_e64 v16, v16, v10
	v_mul_f32_e64 v17, v17, v10
	v_pk_mul_f32 v[2:3], v[2:3], v[10:11] op_sel_hi:[1,0]
	v_pk_mul_f32 v[0:1], v[0:1], v[10:11] op_sel_hi:[1,0]
	v_mfma_f32_16x16x32_bf16 v[4:7], v[140:143], v[128:131], v[4:7]
	ds_read_b64_tr_b16 v[132:133], v229 offset:34816
	ds_read_b64_tr_b16 v[136:137], v230 offset:34816
	ds_read_b64_tr_b16 v[140:141], v231 offset:34816
	ds_read_b64_tr_b16 v[194:195], v232 offset:34816
	ds_read_b64_tr_b16 v[134:135], v229 offset:38912
	ds_read_b64_tr_b16 v[138:139], v230 offset:38912
	ds_read_b64_tr_b16 v[142:143], v231 offset:38912
	ds_read_b64_tr_b16 v[196:197], v232 offset:38912
	s_waitcnt lgkmcnt(8)
	v_mfma_f32_16x16x32_bf16 v[52:55], v[144:147], v[120:123], v[52:55]
	v_mfma_f32_16x16x32_bf16 v[10:13], v[144:147], v[128:131], v[12:15]
	s_waitcnt lgkmcnt(3)
	v_mfma_f32_16x16x32_bf16 v[48:51], v[132:135], v[120:123], v[48:51]
	v_mfma_f32_16x16x32_bf16 v[32:35], v[132:135], v[128:131], v[32:35]
	s_waitcnt lgkmcnt(2)
	v_mfma_f32_16x16x32_bf16 v[44:47], v[136:139], v[120:123], v[44:47]
	v_mfma_f32_16x16x32_bf16 v[24:27], v[136:139], v[128:131], v[24:27]
	s_waitcnt lgkmcnt(1)
	v_mfma_f32_16x16x32_bf16 v[40:43], v[140:143], v[120:123], v[40:43]
	v_mfma_f32_16x16x32_bf16 v[16:19], v[140:143], v[128:131], v[16:19]
	ds_read_b64_tr_b16 v[132:133], v157 offset:43008
	ds_read_b64_tr_b16 v[136:137], v226 offset:43008
	ds_read_b64_tr_b16 v[140:141], v227 offset:43008
	ds_read_b64_tr_b16 v[144:145], v228 offset:43008
	ds_read_b64_tr_b16 v[134:135], v157 offset:47104
	ds_read_b64_tr_b16 v[138:139], v226 offset:47104
	ds_read_b64_tr_b16 v[142:143], v227 offset:47104
	ds_read_b64_tr_b16 v[146:147], v228 offset:47104
	s_waitcnt lgkmcnt(8)
	v_mfma_f32_16x16x32_bf16 v[36:39], v[194:197], v[120:123], v[36:39]
	v_mfma_f32_16x16x32_bf16 v[0:3], v[194:197], v[128:131], v[0:3]
	s_waitcnt lgkmcnt(3)
	v_mfma_f32_16x16x32_bf16 v[64:67], v[132:135], v[116:119], v[64:67]
	v_mfma_f32_16x16x32_bf16 v[28:31], v[132:135], v[124:127], v[28:31]
	s_waitcnt lgkmcnt(2)
	v_mfma_f32_16x16x32_bf16 v[60:63], v[136:139], v[116:119], v[60:63]
	v_mfma_f32_16x16x32_bf16 v[20:23], v[136:139], v[124:127], v[20:23]
	ds_read_b64_tr_b16 v[120:121], v229 offset:43008
	ds_read_b64_tr_b16 v[128:129], v230 offset:43008
	ds_read_b64_tr_b16 v[132:133], v231 offset:43008
	ds_read_b64_tr_b16 v[136:137], v232 offset:43008
	ds_read_b64_tr_b16 v[122:123], v229 offset:47104
	ds_read_b64_tr_b16 v[130:131], v230 offset:47104
	ds_read_b64_tr_b16 v[134:135], v231 offset:47104
	ds_read_b64_tr_b16 v[138:139], v232 offset:47104
	s_waitcnt lgkmcnt(9)
	v_mfma_f32_16x16x32_bf16 v[56:59], v[140:143], v[116:119], v[56:59]
	v_mfma_f32_16x16x32_bf16 v[4:7], v[140:143], v[124:127], v[4:7]
	s_waitcnt lgkmcnt(8)
	v_mfma_f32_16x16x32_bf16 v[52:55], v[144:147], v[116:119], v[52:55]
	v_mfma_f32_16x16x32_bf16 v[12:15], v[144:147], v[124:127], v[10:13]
	s_waitcnt lgkmcnt(3)
	v_mfma_f32_16x16x32_bf16 v[48:51], v[120:123], v[116:119], v[48:51]
	v_mfma_f32_16x16x32_bf16 v[32:35], v[120:123], v[124:127], v[32:35]
	s_waitcnt lgkmcnt(2)
	v_mfma_f32_16x16x32_bf16 v[44:47], v[128:131], v[116:119], v[44:47]
	v_mfma_f32_16x16x32_bf16 v[24:27], v[128:131], v[124:127], v[24:27]
	s_waitcnt lgkmcnt(1)
	v_mfma_f32_16x16x32_bf16 v[40:43], v[132:135], v[116:119], v[40:43]
	v_mfma_f32_16x16x32_bf16 v[16:19], v[132:135], v[124:127], v[16:19]
	s_waitcnt lgkmcnt(0)
	v_mfma_f32_16x16x32_bf16 v[36:39], v[136:139], v[116:119], v[36:39]
	v_mfma_f32_16x16x32_bf16 v[0:3], v[136:139], v[124:127], v[0:3]
	v_mov_b32_e32 v10, v154
	v_mov_b32_e32 v177, v156
	v_mov_b32_e32 v11, v8
	v_mov_b32_e32 v181, v155
.LBB0_912:
	s_add_i32 s40, s7, 1
	s_add_i32 s85, s85, 64
	s_cmp_eq_u32 s7, s6
	s_waitcnt vmcnt(0) lgkmcnt(0)
	s_barrier
	s_cbranch_scc1 .LBB0_914
	s_mov_b32 s7, s40
	s_branch .LBB0_894
